# v55 + P7 per-pass combine epilogue: the 11 o_cmp/o_win piece loads issued up front into registers dead after the block loop (were issued one at a time with vmcnt(0) each), waits recounted
# baseline (speedup 1.0000x reference)
.LBB0_813:
	v_mov_b32_e32 v1, v129
	s_nop 1
	v_permlane32_swap_b32_e32 v129, v1
	v_add_f32_e32 v1, v129, v1
	v_mov_b32_e32 v58, v1
	s_nop 1
	v_permlane16_swap_b32_e32 v1, v58
	s_and_saveexec_b64 s[8:9], s[6:7]
	s_cbranch_execz .LBB0_783
	s_ashr_i32 s11, s45, 31
	s_add_u32 s10, s45, s3
	s_addc_u32 s11, s11, 0
	s_lshl_b64 s[12:13], s[10:11], 7
	v_lshl_add_u64 v[2:3], v[122:123], 0, s[12:13]
	global_load_dword v70, v[2:3], off offset:4
	s_mul_i32 s12, s11, 0x4e00
	s_mul_hi_u32 s13, s10, 0x4e00
	s_add_i32 s13, s13, s12
	s_mul_i32 s12, s10, 0x4e00
	s_add_u32 s12, s94, s12
	s_addc_u32 s13, s95, s13
	v_mov_b32_e32 v129, v0
	v_lshl_add_u64 v[2:3], s[12:13], 0, v[128:129]
	v_lshl_add_u64 v[2:3], v[124:125], 1, v[2:3]
	v_add_co_u32_e32 v62, vcc, s1, v2
	s_lshl_b64 s[10:11], s[10:11], 11
	s_nop 0
	v_addc_co_u32_e32 v63, vcc, 0, v3, vcc
	v_lshl_add_u64 v[56:57], v[126:127], 0, s[10:11]
	global_load_dwordx2 v[62:63], v[62:63], off offset:1024
	v_add_f32_e32 v1, v1, v58
	global_load_dwordx2 v[60:61], v[56:57], off
	v_div_scale_f32 v71, s[10:11], v1, v1, s43
	v_rcp_f32_e32 v72, v71
	v_div_scale_f32 v73, vcc, s43, v1, s43
	v_fma_f32 v58, -v71, v72, 1.0
	v_fmac_f32_e32 v72, v58, v72
	v_mul_f32_e32 v74, v73, v72
	v_fma_f32 v64, -v71, v74, v73
	v_fmac_f32_e32 v74, v64, v72
	v_fma_f32 v71, -v71, v74, v73
	v_div_fmas_f32 v71, v71, v72, v74
	v_div_fixup_f32 v71, v71, v1, s43
	v_cmp_lt_f32_e32 vcc, 0, v1
	v_lshl_add_u64 v[58:59], v[2:3], 0, s[30:31]
	global_load_dwordx2 v[64:65], v[58:59], off offset:32
	global_load_dwordx2 v[66:67], v[58:59], off offset:64
	global_load_dwordx2 v[68:69], v[58:59], off offset:96
	global_load_dwordx2 v[184:185], v[56:57], off offset:32
	global_load_dwordx2 v[186:187], v[56:57], off offset:64
	global_load_dwordx2 v[188:189], v[56:57], off offset:96
	global_load_dwordx2 v[190:191], v[58:59], off offset:128
	global_load_dwordx2 v[192:193], v[56:57], off offset:128
	global_load_dwordx2 v[194:195], v[58:59], off offset:160
	global_load_dwordx2 v[196:197], v[58:59], off offset:192
	global_load_dwordx2 v[198:199], v[58:59], off offset:224
	global_load_dwordx2 v[200:201], v[56:57], off offset:160
	global_load_dwordx2 v[202:203], v[56:57], off offset:192
	global_load_dwordx2 v[204:205], v[56:57], off offset:224
	v_cndmask_b32_e32 v1, 0, v71, vcc
	s_waitcnt vmcnt(16)
	v_mul_f32_e32 v70, 0xbfb8aa3b, v70
	v_exp_f32_e32 v70, v70
	s_waitcnt vmcnt(15)
	v_lshlrev_b32_e32 v73, 16, v62
	v_add_f32_e32 v70, 1.0, v70
	v_rcp_f32_e32 v70, v70
	v_and_b32_e32 v62, 0xffff0000, v62
	s_waitcnt vmcnt(14)
	v_lshlrev_b32_e32 v71, 16, v60
	v_and_b32_e32 v60, 0xffff0000, v60
	v_mul_f32_e32 v1, v1, v70
	v_lshlrev_b32_e32 v74, 16, v63
	v_and_b32_e32 v63, 0xffff0000, v63
	v_fmac_f32_e32 v73, v52, v1
	v_fmac_f32_e32 v62, v53, v1
	v_lshlrev_b32_e32 v72, 16, v61
	v_and_b32_e32 v61, 0xffff0000, v61
	v_fmac_f32_e32 v74, v54, v1
	v_fmac_f32_e32 v63, v55, v1
	v_add_f32_e32 v52, v73, v71
	v_add_f32_e32 v53, v62, v60
	v_add_f32_e32 v54, v74, v72
	v_add_f32_e32 v55, v63, v61
	v_cvt_pk_bf16_f32 v52, v52, v53
	v_cvt_pk_bf16_f32 v53, v54, v55
	global_store_dwordx2 v[2:3], v[52:53], off
	s_waitcnt vmcnt(14)
	v_lshlrev_b32_e32 v54, 16, v64
	v_and_b32_e32 v55, 0xffff0000, v64
	v_lshlrev_b32_e32 v60, 16, v65
	v_and_b32_e32 v61, 0xffff0000, v65
	v_fmac_f32_e32 v54, v48, v1
	v_fmac_f32_e32 v55, v49, v1
	v_fmac_f32_e32 v60, v50, v1
	v_fmac_f32_e32 v61, v51, v1
	s_waitcnt vmcnt(11)
	v_lshlrev_b32_e32 v48, 16, v184
	v_and_b32_e32 v49, 0xffff0000, v184
	v_lshlrev_b32_e32 v50, 16, v185
	v_and_b32_e32 v51, 0xffff0000, v185
	v_add_f32_e32 v48, v54, v48
	v_add_f32_e32 v49, v55, v49
	v_add_f32_e32 v50, v60, v50
	v_add_f32_e32 v51, v61, v51
	v_cvt_pk_bf16_f32 v48, v48, v49
	v_cvt_pk_bf16_f32 v49, v50, v51
	global_store_dwordx2 v[2:3], v[48:49], off offset:32
	v_lshlrev_b32_e32 v50, 16, v66
	v_and_b32_e32 v51, 0xffff0000, v66
	v_lshlrev_b32_e32 v52, 16, v67
	v_and_b32_e32 v53, 0xffff0000, v67
	v_fmac_f32_e32 v50, v44, v1
	v_fmac_f32_e32 v51, v45, v1
	v_fmac_f32_e32 v52, v46, v1
	v_fmac_f32_e32 v53, v47, v1
	s_waitcnt vmcnt(11)
	v_lshlrev_b32_e32 v44, 16, v186
	v_and_b32_e32 v45, 0xffff0000, v186
	v_lshlrev_b32_e32 v46, 16, v187
	v_and_b32_e32 v47, 0xffff0000, v187
	v_add_f32_e32 v44, v50, v44
	v_add_f32_e32 v45, v51, v45
	v_add_f32_e32 v46, v52, v46
	v_add_f32_e32 v47, v53, v47
	v_cvt_pk_bf16_f32 v44, v44, v45
	v_cvt_pk_bf16_f32 v45, v46, v47
	global_store_dwordx2 v[2:3], v[44:45], off offset:64
	s_nop 0
	v_lshlrev_b32_e32 v48, 16, v68
	v_and_b32_e32 v49, 0xffff0000, v68
	v_lshlrev_b32_e32 v50, 16, v69
	v_and_b32_e32 v51, 0xffff0000, v69
	v_fmac_f32_e32 v48, v40, v1
	v_fmac_f32_e32 v49, v41, v1
	v_fmac_f32_e32 v50, v42, v1
	v_fmac_f32_e32 v51, v43, v1
	s_waitcnt vmcnt(11)
	v_lshlrev_b32_e32 v40, 16, v188
	v_and_b32_e32 v41, 0xffff0000, v188
	v_lshlrev_b32_e32 v42, 16, v189
	v_and_b32_e32 v43, 0xffff0000, v189
	v_add_f32_e32 v40, v48, v40
	v_add_f32_e32 v41, v49, v41
	v_add_f32_e32 v42, v50, v42
	v_add_f32_e32 v43, v51, v43
	v_cvt_pk_bf16_f32 v40, v40, v41
	v_cvt_pk_bf16_f32 v41, v42, v43
	global_store_dwordx2 v[2:3], v[40:41], off offset:96
	s_nop 0
	s_waitcnt vmcnt(11)
	v_lshlrev_b32_e32 v50, 16, v190
	v_and_b32_e32 v46, 0xffff0000, v190
	v_lshlrev_b32_e32 v51, 16, v191
	v_and_b32_e32 v47, 0xffff0000, v191
	v_fmac_f32_e32 v50, v36, v1
	v_fmac_f32_e32 v46, v37, v1
	v_fmac_f32_e32 v51, v38, v1
	v_fmac_f32_e32 v47, v39, v1
	s_waitcnt vmcnt(10)
	v_lshlrev_b32_e32 v36, 16, v192
	v_and_b32_e32 v37, 0xffff0000, v192
	v_lshlrev_b32_e32 v38, 16, v193
	v_and_b32_e32 v39, 0xffff0000, v193
	v_add_f32_e32 v36, v50, v36
	v_add_f32_e32 v37, v46, v37
	v_add_f32_e32 v38, v51, v38
	v_add_f32_e32 v39, v47, v39
	v_cvt_pk_bf16_f32 v36, v36, v37
	v_cvt_pk_bf16_f32 v37, v38, v39
	global_store_dwordx2 v[2:3], v[36:37], off offset:128
	s_waitcnt vmcnt(10)
	v_lshlrev_b32_e32 v38, 16, v194
	v_and_b32_e32 v39, 0xffff0000, v194
	v_lshlrev_b32_e32 v40, 16, v195
	v_and_b32_e32 v41, 0xffff0000, v195
	v_fmac_f32_e32 v38, v32, v1
	v_fmac_f32_e32 v39, v33, v1
	v_fmac_f32_e32 v40, v34, v1
	v_fmac_f32_e32 v41, v35, v1
	s_waitcnt vmcnt(7)
	v_lshlrev_b32_e32 v32, 16, v200
	v_and_b32_e32 v33, 0xffff0000, v200
	v_lshlrev_b32_e32 v34, 16, v201
	v_and_b32_e32 v35, 0xffff0000, v201
	v_add_f32_e32 v32, v38, v32
	v_add_f32_e32 v33, v39, v33
	v_add_f32_e32 v34, v40, v34
	v_add_f32_e32 v35, v41, v35
	v_cvt_pk_bf16_f32 v32, v32, v33
	v_cvt_pk_bf16_f32 v33, v34, v35
	global_store_dwordx2 v[2:3], v[32:33], off offset:160
	v_lshlrev_b32_e32 v34, 16, v196
	v_and_b32_e32 v35, 0xffff0000, v196
	v_lshlrev_b32_e32 v36, 16, v197
	v_and_b32_e32 v37, 0xffff0000, v197
	v_fmac_f32_e32 v34, v28, v1
	v_fmac_f32_e32 v35, v29, v1
	v_fmac_f32_e32 v36, v30, v1
	v_fmac_f32_e32 v37, v31, v1
	s_waitcnt vmcnt(7)
	v_lshlrev_b32_e32 v28, 16, v202
	v_and_b32_e32 v29, 0xffff0000, v202
	v_lshlrev_b32_e32 v30, 16, v203
	v_and_b32_e32 v31, 0xffff0000, v203
	v_add_f32_e32 v28, v34, v28
	v_add_f32_e32 v29, v35, v29
	v_add_f32_e32 v30, v36, v30
	v_add_f32_e32 v31, v37, v31
	v_cvt_pk_bf16_f32 v28, v28, v29
	v_cvt_pk_bf16_f32 v29, v30, v31
	global_store_dwordx2 v[2:3], v[28:29], off offset:192
	v_lshlrev_b32_e32 v30, 16, v198
	v_and_b32_e32 v31, 0xffff0000, v198
	v_lshlrev_b32_e32 v32, 16, v199
	v_and_b32_e32 v33, 0xffff0000, v199
	v_fmac_f32_e32 v30, v24, v1
	v_fmac_f32_e32 v31, v25, v1
	v_fmac_f32_e32 v32, v26, v1
	v_fmac_f32_e32 v33, v27, v1
	s_waitcnt vmcnt(7)
	v_and_b32_e32 v24, 0xffff0000, v204
	v_lshlrev_b32_e32 v25, 16, v205
	v_lshlrev_b32_e32 v1, 16, v204
	v_and_b32_e32 v26, 0xffff0000, v205
	v_add_f32_e32 v24, v31, v24
	v_add_f32_e32 v25, v32, v25
	v_add_f32_e32 v1, v30, v1
	v_add_f32_e32 v26, v33, v26
	v_cvt_pk_bf16_f32 v24, v1, v24
	v_cvt_pk_bf16_f32 v25, v25, v26
	global_store_dwordx2 v[2:3], v[24:25], off offset:224
	s_branch .LBB0_783
